# v22
# speedup vs baseline: 1.0181x; 1.0106x over previous
; __device__ __forceinline__ void finishSM(f32x16& p0, f32x16& p1, float alpha, float& l_reg, bf16x8& pa0, bf16x8& pa1, bf16x8& pa2, bf16x8& pa3) {
;     for (int r = 0; r < 16; ++r) p1[r] = __builtin_amdgcn_exp2f(p1[r]);
;     float ps = 0; for (int r = 0; r < 16; ++r) ps += p0[r]; for (int r = 0; r < 16; ++r) ps += p1[r];
;     { auto rr = __builtin_amdgcn_permlane32_swap(__float_as_uint(ps), __float_as_uint(ps), false, false);
;       ps = __uint_as_float(rr[0]) + __uint_as_float(rr[1]); }
;     l_reg = l_reg * alpha + ps;
;     ...
;     PK4(p0, 0, pa0); PK4(p0, 8, pa1); PK4(p1, 0, pa2); PK4(p1, 8, pa3);
;     ...
; }
; template <int KB, bool SK>
; __device__ __forceinline__ void qkt(f32x16& p0, f32x16& p1, const char* K_lds, int r32, int hi, const bf16x8* qr, bool act) {
;     if (SK && !act) { const float NEG = -__builtin_inff();
; #pragma unroll
;         for (int r = 0; r < 16; ++r) { p0[r] = NEG; p1[r] = NEG; } return; }
;     p0 = f32x16{}; p1 = f32x16{};
;     const char* kb[4];
; #pragma unroll
;     for (int dd = 0; dd < 4; ++dd) kb[dd] = K_lds + KB * SHM_K + KSWZ(r32, (dd * 16 + hi * 8) * 2);
; #pragma unroll
;     for (int d0 = 0; d0 < 8; ++d0) { const char* a = kb[d0 & 3] + (d0 >> 2) * 128;
;         bf16x8 b0 = *reinterpret_cast<const bf16x8*>(a);
;         bf16x8 b1 = *reinterpret_cast<const bf16x8*>(a + 32 * 256);
;         p0 = __builtin_amdgcn_mfma_f32_32x32x16_bf16(b0, qr[d0], p0, 0, 0, 0);
;         p1 = __builtin_amdgcn_mfma_f32_32x32x16_bf16(b1, qr[d0], p1, 0, 0, 0); }
; }
.LBB0_205:
	v_add_u32_e32 v188, s74, v160
	v_add_u32_e32 v128, 1, v188
	v_add_u32_e32 v130, 33, v188
	v_ashrrev_i32_e32 v129, 31, v128
	v_ashrrev_i32_e32 v131, 31, v130
	v_lshlrev_b64 v[136:137], 8, v[128:129]
	v_lshlrev_b64 v[138:139], 8, v[130:131]
	v_lshl_add_u64 v[128:129], v[166:167], 0, v[136:137]
	v_lshl_add_u64 v[132:133], v[166:167], 0, v[138:139]
	v_lshl_add_u64 v[136:137], v[168:169], 0, v[136:137]
	v_lshl_add_u64 v[140:141], v[168:169], 0, v[138:139]
	global_load_dwordx4 v[128:131], v[128:129], off
	s_nop 0
	global_load_dwordx4 v[132:135], v[132:133], off
	s_nop 0
	global_load_dwordx4 v[136:139], v[136:137], off
	s_nop 0
	global_load_dwordx4 v[140:143], v[140:141], off
	ds_read_b128 v[64:67], v180 offset:49152
	ds_read_b128 v[68:71], v180 offset:57344
	ds_read_b128 v[224:227], v179 offset:49152
	ds_read_b128 v[248:251], v179 offset:57344
	ds_read_b128 v[216:219], v165 offset:49152
	ds_read_b128 v[220:223], v165 offset:57344
	v_exp_f32_e32 v240, v144
	v_add_f32_e32 v144, 0, v198
	v_add_f32_e32 v144, v199, v144
	v_add_f32_e32 v144, v210, v144
	v_add_f32_e32 v144, v212, v144
	v_add_f32_e32 v144, v213, v144
	s_waitcnt lgkmcnt(5)
	v_mfma_f32_32x32x16_bf16 v[80:95], v[64:67], v[124:127], 0
	v_add_f32_e32 v144, v215, v144
	v_add_f32_e32 v144, v211, v144
	v_add_f32_e32 v144, v214, v144
	v_add_f32_e32 v144, v190, v144
	s_waitcnt lgkmcnt(4)
	v_mfma_f32_32x32x16_bf16 v[64:79], v[68:71], v[124:127], 0
	v_add_f32_e32 v144, v192, v144
	v_add_f32_e32 v144, v193, v144
	v_add_f32_e32 v144, v196, v144
	v_add_f32_e32 v144, v191, v144
	v_add_f32_e32 v144, v194, v144
	v_add_f32_e32 v144, v195, v144
	s_waitcnt lgkmcnt(3)
	v_mfma_f32_32x32x16_bf16 v[80:95], v[224:227], v[120:123], v[80:95]
	v_add_f32_e32 v144, v197, v144
	v_exp_f32_e32 v241, v145
	v_exp_f32_e32 v242, v158
	v_exp_f32_e32 v243, v159
	s_waitcnt lgkmcnt(2)
	v_mfma_f32_32x32x16_bf16 v[64:79], v[248:251], v[120:123], v[64:79]
	ds_read_b128 v[224:227], v163 offset:49152
	ds_read_b128 v[248:251], v163 offset:57344
	v_exp_f32_e32 v244, v152
	v_exp_f32_e32 v245, v153
	v_exp_f32_e32 v246, v146
	v_exp_f32_e32 v247, v147
	v_cvt_pk_bf16_f32 v145, v210, v212
	v_cvt_pk_bf16_f32 v146, v213, v215
	s_waitcnt lgkmcnt(3)
	v_mfma_f32_32x32x16_bf16 v[80:95], v[216:219], v[116:119], v[80:95]
	v_cvt_pk_bf16_f32 v147, v211, v214
	v_cvt_pk_bf16_f32 v158, v244, v245
	v_cvt_pk_bf16_f32 v159, v246, v247
	s_sub_i32 s8, s74, 63
	s_waitcnt lgkmcnt(2)
	v_mfma_f32_32x32x16_bf16 v[64:79], v[220:223], v[116:119], v[64:79]
	ds_read_b128 v[216:219], v180 offset:49280
	ds_read_b128 v[220:223], v180 offset:57472
	v_permlane32_swap_b32_e32 v145, v147
	v_exp_f32_e32 v228, v156
	v_exp_f32_e32 v229, v157
	v_exp_f32_e32 v252, v154
	v_exp_f32_e32 v253, v155
	v_add_f32_e32 v144, v228, v144
	s_waitcnt lgkmcnt(3)
	v_mfma_f32_32x32x16_bf16 v[80:95], v[224:227], v[112:115], v[80:95]
	v_add_f32_e32 v144, v229, v144
	v_add_f32_e32 v144, v252, v144
	v_add_f32_e32 v144, v253, v144
	v_cvt_pk_bf16_f32 v152, v228, v229
	s_waitcnt lgkmcnt(2)
	v_mfma_f32_32x32x16_bf16 v[64:79], v[248:251], v[112:115], v[64:79]
	ds_read_b128 v[224:227], v179 offset:49280
	ds_read_b128 v[248:251], v179 offset:57472
	v_cvt_pk_bf16_f32 v153, v252, v253
	v_exp_f32_e32 v228, v150
	v_exp_f32_e32 v229, v151
	v_exp_f32_e32 v252, v148
	v_exp_f32_e32 v253, v149
	v_add_f32_e32 v144, v228, v144
	s_waitcnt lgkmcnt(3)
	v_mfma_f32_32x32x16_bf16 v[80:95], v[216:219], v[108:111], v[80:95]
	v_add_f32_e32 v144, v229, v144
	v_add_f32_e32 v144, v252, v144
	v_add_f32_e32 v144, v253, v144
	v_cvt_pk_bf16_f32 v154, v228, v229
	s_waitcnt lgkmcnt(2)
	v_mfma_f32_32x32x16_bf16 v[64:79], v[220:223], v[108:111], v[64:79]
	ds_read_b128 v[216:219], v165 offset:49280
	ds_read_b128 v[220:223], v165 offset:57472
	v_cvt_pk_bf16_f32 v155, v252, v253
	v_add_f32_e32 v144, v240, v144
	v_add_f32_e32 v144, v241, v144
	v_add_f32_e32 v144, v242, v144
	v_add_f32_e32 v144, v243, v144
	v_add_f32_e32 v144, v244, v144
	s_waitcnt lgkmcnt(3)
	v_mfma_f32_32x32x16_bf16 v[80:95], v[224:227], v[104:107], v[80:95]
	v_add_f32_e32 v144, v245, v144
	v_add_f32_e32 v144, v246, v144
	v_add_f32_e32 v186, v247, v144
	v_mov_b32_e32 v187, v186
	s_waitcnt lgkmcnt(2)
	v_mfma_f32_32x32x16_bf16 v[64:79], v[248:251], v[104:107], v[64:79]
	ds_read_b128 v[224:227], v163 offset:49280
	ds_read_b128 v[248:251], v163 offset:57472
	s_nop 1
	v_permlane32_swap_b32_e32 v186, v187
	v_cvt_pk_bf16_f32 v144, v198, v199
	v_cvt_pk_bf16_f32 v148, v190, v192
	v_cvt_pk_bf16_f32 v149, v193, v196
	v_cvt_pk_bf16_f32 v150, v191, v194
	s_waitcnt lgkmcnt(3)
	v_mfma_f32_32x32x16_bf16 v[80:95], v[216:219], v[100:103], v[80:95]
	v_cvt_pk_bf16_f32 v151, v195, v197
	v_cvt_pk_bf16_f32 v156, v240, v241
	v_cvt_pk_bf16_f32 v157, v242, v243
	v_permlane32_swap_b32_e32 v144, v146
	s_waitcnt lgkmcnt(2)
	v_mfma_f32_32x32x16_bf16 v[64:79], v[220:223], v[100:103], v[64:79]
	v_permlane32_swap_b32_e32 v148, v150
	v_permlane32_swap_b32_e32 v149, v151
	v_permlane32_swap_b32_e32 v152, v154
	v_permlane32_swap_b32_e32 v153, v155
	v_permlane32_swap_b32_e32 v156, v158
	v_permlane32_swap_b32_e32 v157, v159
	s_waitcnt lgkmcnt(1)
	v_mfma_f32_32x32x16_bf16 v[80:95], v[224:227], v[96:99], v[80:95]
	s_waitcnt lgkmcnt(0)
	v_mfma_f32_32x32x16_bf16 v[64:79], v[248:251], v[96:99], v[64:79]
	s_cmp_le_i32 s74, s70
	s_cselect_b64 s[42:43], -1, 0
	s_cmp_gt_i32 s8, s72
	s_cselect_b64 s[8:9], -1, 0
	s_and_b64 s[8:9], s[42:43], s[8:9]
	s_and_b64 vcc, exec, s[8:9]
	s_cbranch_vccnz .Lmy_h1_pv
; __device__ __forceinline__ void mask_tile(f32x16& p0, f32x16& p1, int dq, unsigned W) {
;     const float NEG = -__builtin_inff();
; #pragma unroll
;     for (int r = 0; r < 16; ++r) {
;         const int c = (r & 3) + 8 * (r >> 2);
;         if ((unsigned)(dq - c) >= W) p0[r] = NEG;
;         if ((unsigned)(dq - c - 32) >= W) p1[r] = NEG;
;     }
; }
	v_add_u32_e32 v239, 0x207b, v185
	v_cmp_gt_u32_e32 vcc, s62, v239
	v_add_u32_e32 v239, 0x5b, v185
	s_nop 0
	v_cndmask_b32_e32 v80, v235, v80, vcc
	v_cmp_lt_u32_e32 vcc, s65, v239
	v_add_u32_e32 v239, 0x7a, v185
	s_nop 0
	v_cndmask_b32_e32 v64, v235, v64, vcc
	v_cmp_lt_u32_e32 vcc, s65, v239
	v_add_u32_e32 v239, 0x5a, v185
	s_nop 0
	v_cndmask_b32_e32 v81, v235, v81, vcc
	v_cmp_lt_u32_e32 vcc, s65, v239
	v_add_u32_e32 v239, 0x79, v185
	s_nop 0
	v_cndmask_b32_e32 v65, v235, v65, vcc
	v_cmp_lt_u32_e32 vcc, s65, v239
	v_add_u32_e32 v239, 0x59, v185
	s_nop 0
	v_cndmask_b32_e32 v82, v235, v82, vcc
	v_cmp_lt_u32_e32 vcc, s65, v239
	v_add_u32_e32 v239, 0x78, v185
	s_nop 0
	v_cndmask_b32_e32 v66, v235, v66, vcc
	v_cmp_lt_u32_e32 vcc, s65, v239
	v_add_u32_e32 v239, 0x58, v185
	s_nop 0
	v_cndmask_b32_e32 v83, v235, v83, vcc
	v_cmp_lt_u32_e32 vcc, s65, v239
	v_add_u32_e32 v239, 0x73, v185
	s_nop 0
	v_cndmask_b32_e32 v67, v235, v67, vcc
	v_cmp_lt_u32_e32 vcc, s65, v239
	v_add_u32_e32 v239, 0x53, v185
	s_nop 0
	v_cndmask_b32_e32 v84, v235, v84, vcc
	v_cmp_lt_u32_e32 vcc, s65, v239
	v_add_u32_e32 v239, 0x72, v185
	s_nop 0
	v_cndmask_b32_e32 v68, v235, v68, vcc
	v_cmp_lt_u32_e32 vcc, s65, v239
	v_add_u32_e32 v239, 0x52, v185
	s_nop 0
	v_cndmask_b32_e32 v85, v235, v85, vcc
	v_cmp_lt_u32_e32 vcc, s65, v239
	v_add_u32_e32 v239, 0x71, v185
	s_nop 0
	v_cndmask_b32_e32 v69, v235, v69, vcc
	v_cmp_lt_u32_e32 vcc, s65, v239
	v_add_u32_e32 v239, 0x51, v185
	s_nop 0
	v_cndmask_b32_e32 v86, v235, v86, vcc
	v_cmp_lt_u32_e32 vcc, s65, v239
	v_add_u32_e32 v239, 0x70, v185
	s_nop 0
	v_cndmask_b32_e32 v70, v235, v70, vcc
	v_cmp_lt_u32_e32 vcc, s65, v239
	v_add_u32_e32 v239, 0x50, v185
	s_nop 0
	v_cndmask_b32_e32 v87, v235, v87, vcc
	v_cmp_lt_u32_e32 vcc, s65, v239
	v_add_u32_e32 v239, 0x6b, v185
	s_nop 0
	v_cndmask_b32_e32 v71, v235, v71, vcc
	v_cmp_lt_u32_e32 vcc, s65, v239
	v_add_u32_e32 v239, 0x4b, v185
	s_nop 0
	v_cndmask_b32_e32 v88, v235, v88, vcc
	v_cmp_lt_u32_e32 vcc, s65, v239
	v_add_u32_e32 v239, 0x6a, v185
	s_nop 0
	v_cndmask_b32_e32 v72, v235, v72, vcc
	v_cmp_lt_u32_e32 vcc, s65, v239
	v_add_u32_e32 v239, 0x4a, v185
	s_nop 0
	v_cndmask_b32_e32 v89, v235, v89, vcc
	v_cmp_lt_u32_e32 vcc, s65, v239
	v_add_u32_e32 v239, 0x69, v185
	s_nop 0
	v_cndmask_b32_e32 v73, v235, v73, vcc
	v_cmp_lt_u32_e32 vcc, s65, v239
	v_add_u32_e32 v239, 0x49, v185
	s_nop 0
	v_cndmask_b32_e32 v90, v235, v90, vcc
	v_cmp_lt_u32_e32 vcc, s65, v239
	v_add_u32_e32 v239, 0x68, v185
	s_nop 0
	v_cndmask_b32_e32 v74, v235, v74, vcc
	v_cmp_lt_u32_e32 vcc, s65, v239
	v_add_u32_e32 v239, 0x48, v185
	s_nop 0
	v_cndmask_b32_e32 v91, v235, v91, vcc
	v_cmp_lt_u32_e32 vcc, s65, v239
	v_add_u32_e32 v239, 0x63, v185
	s_nop 0
	v_cndmask_b32_e32 v75, v235, v75, vcc
	v_cmp_lt_u32_e32 vcc, s65, v239
	v_add_u32_e32 v239, 0x43, v185
	s_nop 0
	v_cndmask_b32_e32 v92, v235, v92, vcc
	v_cmp_lt_u32_e32 vcc, s65, v239
	v_add_u32_e32 v239, 0x62, v185
	s_nop 0
	v_cndmask_b32_e32 v76, v235, v76, vcc
	v_cmp_lt_u32_e32 vcc, s65, v239
	v_add_u32_e32 v239, 0x42, v185
	s_nop 0
	v_cndmask_b32_e32 v93, v235, v93, vcc
	v_cmp_lt_u32_e32 vcc, s65, v239
	v_add_u32_e32 v239, 0x61, v185
	s_nop 0
	v_cndmask_b32_e32 v77, v235, v77, vcc
	v_cmp_lt_u32_e32 vcc, s65, v239
	v_add_u32_e32 v239, 0x41, v185
	s_nop 0
	v_cndmask_b32_e32 v94, v235, v94, vcc
	v_cmp_lt_u32_e32 vcc, s65, v239
	v_add_u32_e32 v239, 0x60, v185
	s_nop 0
	v_cndmask_b32_e32 v78, v235, v78, vcc
	v_cmp_lt_u32_e32 vcc, s65, v239
	v_add_u32_e32 v239, 64, v185
	s_nop 0
	v_cndmask_b32_e32 v95, v235, v95, vcc
	v_cmp_lt_u32_e32 vcc, s65, v239
	s_nop 1
	v_cndmask_b32_e32 v79, v235, v79, vcc

; __device__ __forceinline__ void finishSM(f32x16& p0, f32x16& p1, float alpha, float& l_reg, bf16x8& pa0, bf16x8& pa1, bf16x8& pa2, bf16x8& pa3) {
;     for (int r = 0; r < 16; ++r) p1[r] = __builtin_amdgcn_exp2f(p1[r]);
;     float ps = 0; for (int r = 0; r < 16; ++r) ps += p0[r]; for (int r = 0; r < 16; ++r) ps += p1[r];
; template <int KB, bool SK>
; __device__ __forceinline__ void qkt(f32x16& p0, f32x16& p1, const char* K_lds, int r32, int hi, const bf16x8* qr, bool act) {
;     if (SK && !act) { const float NEG = -__builtin_inff();
; #pragma unroll
;         for (int r = 0; r < 16; ++r) { p0[r] = NEG; p1[r] = NEG; } return; }
;     p0 = f32x16{}; p1 = f32x16{};
;     const char* kb[4];
; #pragma unroll
;     for (int dd = 0; dd < 4; ++dd) kb[dd] = K_lds + KB * SHM_K + KSWZ(r32, (dd * 16 + hi * 8) * 2);
; #pragma unroll
;     for (int d0 = 0; d0 < 8; ++d0) { const char* a = kb[d0 & 3] + (d0 >> 2) * 128;
;         bf16x8 b0 = *reinterpret_cast<const bf16x8*>(a);
;         bf16x8 b1 = *reinterpret_cast<const bf16x8*>(a + 32 * 256);
;         p0 = __builtin_amdgcn_mfma_f32_32x32x16_bf16(b0, qr[d0], p0, 0, 0, 0);
;         p1 = __builtin_amdgcn_mfma_f32_32x32x16_bf16(b1, qr[d0], p1, 0, 0, 0); }
; }
.Lmy_h2_ld:
	ds_read_b128 v[64:67], v180 offset:32768
	ds_read_b128 v[68:71], v180 offset:40960
	ds_read_b128 v[216:219], v179 offset:32768
	ds_read_b128 v[220:223], v179 offset:40960
	ds_read_b128 v[224:227], v165 offset:32768
	ds_read_b128 v[248:251], v165 offset:40960
	v_exp_f32_e32 v199, v199
	v_exp_f32_e32 v210, v210
	v_exp_f32_e32 v211, v211
	v_exp_f32_e32 v212, v212
	v_exp_f32_e32 v213, v213
	v_exp_f32_e32 v192, v192
	s_waitcnt lgkmcnt(5)
	v_mfma_f32_32x32x16_bf16 v[80:95], v[64:67], v[124:127], 0
	v_exp_f32_e32 v193, v193
	v_exp_f32_e32 v194, v194
	v_exp_f32_e32 v195, v195
	s_waitcnt lgkmcnt(4)
	v_mfma_f32_32x32x16_bf16 v[64:79], v[68:71], v[124:127], 0
	v_exp_f32_e32 v196, v196
	v_exp_f32_e32 v197, v197
	v_exp_f32_e32 v198, v198
	v_exp_f32_e32 v191, v191
	v_exp_f32_e32 v214, v214
	v_exp_f32_e32 v215, v215
	s_waitcnt lgkmcnt(3)
	v_mfma_f32_32x32x16_bf16 v[80:95], v[216:219], v[120:123], v[80:95]
	v_exp_f32_e32 v190, v190
	v_add_f32_e32 v239, 0, v144
	v_add_f32_e32 v239, v145, v239
	s_waitcnt lgkmcnt(2)
	v_mfma_f32_32x32x16_bf16 v[64:79], v[220:223], v[120:123], v[64:79]
	ds_read_b128 v[216:219], v163 offset:32768
	ds_read_b128 v[220:223], v163 offset:40960
	v_add_f32_e32 v239, v146, v239
	v_add_f32_e32 v239, v157, v239
	v_add_f32_e32 v239, v158, v239
	v_add_f32_e32 v239, v159, v239
	v_add_f32_e32 v239, v147, v239
	v_add_f32_e32 v239, v156, v239
	s_waitcnt lgkmcnt(3)
	v_mfma_f32_32x32x16_bf16 v[80:95], v[224:227], v[116:119], v[80:95]
	v_add_f32_e32 v239, v148, v239
	v_add_f32_e32 v239, v149, v239
	v_add_f32_e32 v239, v154, v239
	s_waitcnt lgkmcnt(2)
	v_mfma_f32_32x32x16_bf16 v[64:79], v[248:251], v[116:119], v[64:79]
	ds_read_b128 v[224:227], v180 offset:32896
	ds_read_b128 v[248:251], v180 offset:41088
	v_add_f32_e32 v239, v155, v239
	v_add_f32_e32 v239, v150, v239
	v_add_f32_e32 v239, v151, v239
	v_add_f32_e32 v239, v152, v239
	v_add_f32_e32 v239, v153, v239
	v_add_f32_e32 v239, v199, v239
	s_waitcnt lgkmcnt(3)
	v_mfma_f32_32x32x16_bf16 v[80:95], v[216:219], v[112:115], v[80:95]
	v_add_f32_e32 v239, v210, v239
	v_add_f32_e32 v239, v211, v239
	v_add_f32_e32 v239, v212, v239
	s_waitcnt lgkmcnt(2)
	v_mfma_f32_32x32x16_bf16 v[64:79], v[220:223], v[112:115], v[64:79]
	ds_read_b128 v[216:219], v179 offset:32896
	ds_read_b128 v[220:223], v179 offset:41088
	v_add_f32_e32 v239, v213, v239
	v_add_f32_e32 v239, v192, v239
	v_add_f32_e32 v239, v193, v239
	v_add_f32_e32 v239, v194, v239
	v_add_f32_e32 v239, v195, v239
	v_add_f32_e32 v239, v196, v239
	s_waitcnt lgkmcnt(3)
	v_mfma_f32_32x32x16_bf16 v[80:95], v[224:227], v[108:111], v[80:95]
	v_add_f32_e32 v239, v197, v239
	v_add_f32_e32 v239, v198, v239
	v_add_f32_e32 v239, v191, v239
	s_waitcnt lgkmcnt(2)
	v_mfma_f32_32x32x16_bf16 v[64:79], v[248:251], v[108:111], v[64:79]
	ds_read_b128 v[224:227], v165 offset:32896
	ds_read_b128 v[248:251], v165 offset:41088
	v_add_f32_e32 v239, v214, v239
	v_add_f32_e32 v239, v215, v239
	v_cvt_pk_bf16_f32 v144, v144, v145
	v_cvt_pk_bf16_f32 v145, v146, v157
	v_cvt_pk_bf16_f32 v146, v158, v159
	v_cvt_pk_bf16_f32 v147, v147, v156
	s_waitcnt lgkmcnt(3)
	v_mfma_f32_32x32x16_bf16 v[80:95], v[216:219], v[104:107], v[80:95]
	v_cvt_pk_bf16_f32 v148, v148, v149
	v_cvt_pk_bf16_f32 v149, v154, v155
	v_cvt_pk_bf16_f32 v150, v150, v151
	s_waitcnt lgkmcnt(2)
	v_mfma_f32_32x32x16_bf16 v[64:79], v[220:223], v[104:107], v[64:79]
	ds_read_b128 v[216:219], v163 offset:32896
	ds_read_b128 v[220:223], v163 offset:41088
	v_cvt_pk_bf16_f32 v151, v152, v153
	v_cvt_pk_bf16_f32 v152, v199, v210
	v_cvt_pk_bf16_f32 v153, v211, v212
	v_cvt_pk_bf16_f32 v154, v213, v192
	v_cvt_pk_bf16_f32 v155, v193, v194
	v_cvt_pk_bf16_f32 v156, v195, v196
	s_waitcnt lgkmcnt(3)
	v_mfma_f32_32x32x16_bf16 v[80:95], v[224:227], v[100:103], v[80:95]
	v_cvt_pk_bf16_f32 v157, v197, v198
	v_cvt_pk_bf16_f32 v158, v191, v214
	v_cvt_pk_bf16_f32 v159, v215, v190
	s_waitcnt lgkmcnt(2)
	v_mfma_f32_32x32x16_bf16 v[64:79], v[248:251], v[100:103], v[64:79]
	v_permlane32_swap_b32_e32 v144, v146
	v_permlane32_swap_b32_e32 v145, v147
	v_permlane32_swap_b32_e32 v148, v150
	v_permlane32_swap_b32_e32 v149, v151
	v_permlane32_swap_b32_e32 v152, v154
	v_permlane32_swap_b32_e32 v153, v155
	s_waitcnt lgkmcnt(1)
	v_mfma_f32_32x32x16_bf16 v[80:95], v[216:219], v[96:99], v[80:95]
	v_add_f32_e32 v216, v190, v239
	v_mov_b32_e32 v217, v216
	v_permlane32_swap_b32_e32 v156, v158
	v_permlane32_swap_b32_e32 v157, v159
	s_waitcnt lgkmcnt(0)
	v_mfma_f32_32x32x16_bf16 v[64:79], v[220:223], v[96:99], v[64:79]
	s_nop 1
	v_permlane32_swap_b32_e32 v216, v217
